# MLA loop merged scheduling region (two barriers kept) on top of GQA changes
# speedup vs baseline: 1.0101x; 1.0045x over previous
.LBB0_762:
	ds_read_b128 v[64:67], v189 offset:49152
	ds_read_b128 v[68:71], v189 offset:57344
	ds_read_b128 v[236:239], v191 offset:49152
	ds_read_b128 v[240:243], v191 offset:57344
	ds_read_b128 v[244:247], v193 offset:49152
	ds_read_b128 v[248:251], v193 offset:57344
	s_add_i32 s9, s24, -1
	s_cmp_lt_u32 s9, 3
	s_cselect_b32 s100, s46, s68
	s_add_i32 s100, s100, s8
	s_ashr_i32 s101, s100, 31
	s_add_i32 s0, 0, 0x12800
	s_waitcnt lgkmcnt(5)
	v_mfma_f32_32x32x16_bf16 v[80:95], v[64:67], v[124:127], 0
	v_exp_f32_e32 v140, v140
	v_exp_f32_e32 v141, v141
	v_add_u32_e32 v211, s0, v198
	s_waitcnt lgkmcnt(4)
	v_mfma_f32_32x32x16_bf16 v[64:79], v[68:71], v[124:127], 0
	v_exp_f32_e32 v138, v138
	v_exp_f32_e32 v139, v139
	v_add_u32_e32 v210, s0, v200
	s_waitcnt lgkmcnt(3)
	v_mfma_f32_32x32x16_bf16 v[80:95], v[236:239], v[120:123], v[80:95]
	ds_read_b128 v[236:239], v195 offset:49152
	v_exp_f32_e32 v214, v130
	v_exp_f32_e32 v215, v131
	v_add_u32_e32 v216, s0, v202
	s_waitcnt lgkmcnt(3)
	v_mfma_f32_32x32x16_bf16 v[64:79], v[240:243], v[120:123], v[64:79]
	ds_read_b128 v[240:243], v195 offset:57344
	v_exp_f32_e32 v142, v142
	v_exp_f32_e32 v143, v143
	v_add_u32_e32 v217, s0, v204
	s_waitcnt lgkmcnt(3)
	v_mfma_f32_32x32x16_bf16 v[80:95], v[244:247], v[116:119], v[80:95]
	ds_read_b128 v[244:247], v196 offset:49152
	v_exp_f32_e32 v136, v136
	v_exp_f32_e32 v137, v137
	v_cvt_pk_bf16_f32 v130, v156, v158
	s_waitcnt lgkmcnt(3)
	v_mfma_f32_32x32x16_bf16 v[64:79], v[248:251], v[116:119], v[64:79]
	ds_read_b128 v[248:251], v196 offset:57344
	v_exp_f32_e32 v212, v132
	v_exp_f32_e32 v213, v133
	v_cvt_pk_bf16_f32 v131, v154, v155
	s_waitcnt lgkmcnt(3)
	v_mfma_f32_32x32x16_bf16 v[80:95], v[236:239], v[112:115], v[80:95]
	ds_read_b128 v[236:239], v194 offset:49152
	v_exp_f32_e32 v220, v128
	v_add_f32_e32 v128, 0, v159
	v_add_f32_e32 v128, v161, v128
	v_add_f32_e32 v128, v157, v128
	s_waitcnt lgkmcnt(3)
	v_mfma_f32_32x32x16_bf16 v[64:79], v[240:243], v[112:115], v[64:79]
	ds_read_b128 v[240:243], v194 offset:57344
	v_add_f32_e32 v128, v160, v128
	v_add_f32_e32 v128, v156, v128
	v_add_f32_e32 v128, v158, v128
	v_add_f32_e32 v128, v154, v128
	v_add_f32_e32 v128, v155, v128
	s_waitcnt lgkmcnt(3)
	v_mfma_f32_32x32x16_bf16 v[80:95], v[244:247], v[108:111], v[80:95]
	ds_read_b128 v[244:247], v192 offset:49152
	v_add_f32_e32 v128, v151, v128
	v_add_f32_e32 v128, v153, v128
	v_add_f32_e32 v128, v150, v128
	v_add_f32_e32 v128, v152, v128
	v_add_f32_e32 v128, v147, v128
	s_waitcnt lgkmcnt(3)
	v_mfma_f32_32x32x16_bf16 v[64:79], v[248:251], v[108:111], v[64:79]
	ds_read_b128 v[248:251], v192 offset:57344
	v_add_f32_e32 v128, v149, v128
	v_add_f32_e32 v128, v146, v128
	v_add_f32_e32 v128, v148, v128
	v_add_f32_e32 v128, v140, v128
	v_add_f32_e32 v128, v141, v128
	s_waitcnt lgkmcnt(3)
	v_mfma_f32_32x32x16_bf16 v[80:95], v[236:239], v[104:107], v[80:95]
	ds_read_b128 v[236:239], v190 offset:49152
	v_add_f32_e32 v128, v138, v128
	v_add_f32_e32 v128, v139, v128
	v_add_f32_e32 v128, v212, v128
	v_exp_f32_e32 v221, v129
	s_waitcnt lgkmcnt(3)
	v_mfma_f32_32x32x16_bf16 v[64:79], v[240:243], v[104:107], v[64:79]
	ds_read_b128 v[240:243], v190 offset:57344
	v_add_f32_e32 v128, v213, v128
	v_add_f32_e32 v128, v214, v128
	v_add_f32_e32 v128, v215, v128
	v_add_f32_e32 v128, v220, v128
	v_add_f32_e32 v128, v221, v128
	s_waitcnt lgkmcnt(3)
	v_mfma_f32_32x32x16_bf16 v[80:95], v[244:247], v[100:103], v[80:95]
	ds_read_b128 v[244:247], v211
	v_exp_f32_e32 v223, v134
	v_add_f32_e32 v128, v142, v128
	v_exp_f32_e32 v224, v135
	s_waitcnt lgkmcnt(3)
	v_mfma_f32_32x32x16_bf16 v[64:79], v[248:251], v[100:103], v[64:79]
	v_add_f32_e32 v128, v143, v128
	v_add_f32_e32 v128, v136, v128
	v_add_f32_e32 v128, v137, v128
	v_add_f32_e32 v128, v223, v128
	v_add_f32_e32 v218, v224, v128
	s_waitcnt lgkmcnt(2)
	v_mfma_f32_32x32x16_bf16 v[80:95], v[236:239], v[96:99], v[80:95]
	ds_read_b128 v[236:239], v211 offset:4096
	ds_read_b128 v[248:251], v182
	v_mov_b32_e32 v219, v218
	v_cvt_pk_bf16_f32 v128, v159, v161
	v_cvt_pk_bf16_f32 v129, v157, v160
	v_cvt_pk_bf16_f32 v132, v151, v153
	v_cvt_pk_bf16_f32 v133, v150, v152
	s_waitcnt lgkmcnt(3)
	v_mfma_f32_32x32x16_bf16 v[64:79], v[240:243], v[96:99], v[64:79]
	ds_read_b128 v[240:243], v210
	v_cvt_pk_bf16_f32 v134, v147, v149
	v_cvt_pk_bf16_f32 v135, v146, v148
	v_cvt_pk_bf16_f32 v154, v140, v141
	v_cvt_pk_bf16_f32 v155, v138, v139
	v_cvt_pk_bf16_f32 v156, v212, v213
	s_waitcnt lgkmcnt(1)
	v_mfma_f32_32x32x16_bf16 v[80:95], v[244:247], v[248:251], v[80:95]
	v_cvt_pk_bf16_f32 v157, v214, v215
	v_cvt_pk_bf16_f32 v220, v220, v221
	v_cvt_pk_bf16_f32 v221, v142, v143
	v_cvt_pk_bf16_f32 v222, v136, v137
	v_permlane32_swap_b32_e32 v218, v219
	v_mfma_f32_32x32x16_bf16 v[64:79], v[236:239], v[248:251], v[64:79]
	ds_read_b128 v[248:251], v210 offset:4096
	ds_read_b128 v[244:247], v182 offset:1024
	ds_read_b128 v[236:239], v216
	v_permlane32_swap_b32_e32 v128, v130
	v_cvt_pk_bf16_f32 v223, v223, v224
	v_permlane32_swap_b32_e32 v220, v222
	v_permlane32_swap_b32_e32 v129, v131
	v_permlane32_swap_b32_e32 v132, v134
	s_waitcnt lgkmcnt(1)
	v_mfma_f32_32x32x16_bf16 v[80:95], v[240:243], v[244:247], v[80:95]
	v_permlane32_swap_b32_e32 v133, v135
	v_permlane32_swap_b32_e32 v154, v156
	v_permlane32_swap_b32_e32 v155, v157
	v_permlane32_swap_b32_e32 v221, v223
	v_lshl_add_u64 v[136:137], s[100:101], 0, v[162:163]
	v_mfma_f32_32x32x16_bf16 v[64:79], v[248:251], v[244:247], v[64:79]
	ds_read_b128 v[244:247], v216 offset:4096
	ds_read_b128 v[240:243], v182 offset:2048
	ds_read_b128 v[248:251], v217
	v_mul_lo_u32 v138, v137, s40
	v_mul_lo_u32 v139, v136, s41
	v_mad_u64_u32 v[136:137], s[6:7], v136, s40, 0
	v_add3_u32 v137, v137, v139, v138
	v_lshl_add_u64 v[138:139], v[166:167], 0, s[100:101]
	s_waitcnt lgkmcnt(1)
	v_mfma_f32_32x32x16_bf16 v[80:95], v[236:239], v[240:243], v[80:95]
	v_mul_lo_u32 v140, v139, s40
	v_mul_lo_u32 v141, v138, s41
	v_mad_u64_u32 v[138:139], s[6:7], v138, s40, 0
	v_add3_u32 v139, v139, v141, v140
	v_lshlrev_b64 v[146:147], 1, v[136:137]
	v_mfma_f32_32x32x16_bf16 v[64:79], v[244:247], v[240:243], v[64:79]
	ds_read_b128 v[240:243], v217 offset:4096
	ds_read_b128 v[236:239], v182 offset:3072
	ds_read_b64_tr_b16 v[224:225], v181 offset:0
	ds_read_b64_tr_b16 v[226:227], v181 offset:0x800
	ds_read_b64_tr_b16 v[232:233], v181 offset:0x1000
	ds_read_b64_tr_b16 v[234:235], v181 offset:0x1800
	v_lshlrev_b64 v[148:149], 1, v[138:139]
	v_lshl_add_u64 v[158:159], s[100:101], 0, v[164:165]
	v_lshl_add_u64 v[136:137], v[168:169], 0, v[146:147]
	v_lshl_add_u64 v[140:141], v[168:169], 0, v[148:149]
	v_lshl_add_u64 v[146:147], v[170:171], 0, v[146:147]
	s_waitcnt lgkmcnt(4)
	v_mfma_f32_32x32x16_bf16 v[80:95], v[248:251], v[236:239], v[80:95]
	v_lshl_add_u64 v[150:151], v[170:171], 0, v[148:149]
	v_mad_u64_u32 v[160:161], s[100:101], v158, s3, v[172:173]
	v_mad_i32_i24 v161, v159, s3, v161
	v_mfma_f32_32x32x16_bf16 v[64:79], v[240:243], v[236:239], v[64:79]
	ds_read_b64_tr_b16 v[236:237], v181 offset:0x2000
	ds_read_b64_tr_b16 v[238:239], v181 offset:0x2800
	ds_read_b64_tr_b16 v[240:241], v181 offset:0x3000
	ds_read_b64_tr_b16 v[242:243], v181 offset:0x3800
	ds_read_b64_tr_b16 v[212:213], v181 offset:0x200
	ds_read_b64_tr_b16 v[214:215], v181 offset:0xa00
	global_load_dwordx4 v[136:139], v[136:137], off
	global_load_dwordx4 v[140:143], v[140:141], off
	global_load_dwordx4 v[146:149], v[146:147], off
	global_load_dwordx4 v[150:153], v[150:151], off
	global_load_dwordx4 v[158:161], v[160:161], off
	s_waitcnt lgkmcnt(8)
	v_mfma_f32_32x32x16_bf16 v[0:15], v[128:131], v[224:227], v[0:15]
	ds_read_b64_tr_b16 v[224:225], v181 offset:0x1200
	ds_read_b64_tr_b16 v[226:227], v181 offset:0x1a00
	v_max_f32_e32 v250, v81, v81
	v_max_f32_e32 v251, v80, v80
	v_max_f32_e32 v250, v251, v250
	v_max3_f32 v250, v250, v82, v83
	v_max3_f32 v250, v250, v84, v85
	s_waitcnt lgkmcnt(8)
	v_mfma_f32_32x32x16_bf16 v[0:15], v[132:135], v[232:235], v[0:15]
	ds_read_b64_tr_b16 v[232:233], v181 offset:0x2200
	ds_read_b64_tr_b16 v[234:235], v181 offset:0x2a00
	v_max3_f32 v250, v250, v86, v87
	v_max3_f32 v250, v250, v88, v89
	v_max3_f32 v250, v250, v90, v91
	v_max3_f32 v250, v250, v92, v93
	v_max3_f32 v250, v250, v94, v95
	s_waitcnt lgkmcnt(8)
	v_mfma_f32_32x32x16_bf16 v[0:15], v[154:157], v[236:239], v[0:15]
	ds_read_b64_tr_b16 v[236:237], v181 offset:0x3200
	ds_read_b64_tr_b16 v[238:239], v181 offset:0x3a00
	v_max3_f32 v250, v250, v64, v65
	v_max3_f32 v250, v250, v66, v67
	v_max3_f32 v250, v250, v68, v69
	v_max3_f32 v250, v250, v70, v71
	v_max3_f32 v250, v250, v72, v73
	s_waitcnt lgkmcnt(8)
	v_mfma_f32_32x32x16_bf16 v[0:15], v[220:223], v[240:243], v[0:15]
	ds_read_b64_tr_b16 v[240:241], v181 offset:0x400
	ds_read_b64_tr_b16 v[242:243], v181 offset:0xc00
	v_max3_f32 v250, v250, v74, v75
	v_max3_f32 v250, v250, v76, v77
	v_max3_f32 v250, v250, v78, v79
	v_mov_b32_e32 v251, v250
	s_nop 1
	v_permlane32_swap_b32_e32 v250, v251
	s_waitcnt lgkmcnt(8)
	v_mfma_f32_32x32x16_bf16 v[48:63], v[128:131], v[212:215], v[48:63]
	ds_read_b64_tr_b16 v[212:213], v181 offset:0x1400
	ds_read_b64_tr_b16 v[214:215], v181 offset:0x1c00
	v_max_f32_e32 v251, v251, v251
	v_max_f32_e32 v250, v250, v250
	v_max_f32_e32 v250, v250, v251
	v_sub_f32_e32 v251, v250, v207
	v_cmp_ge_f32_e32 vcc, s94, v251
	s_waitcnt lgkmcnt(8)
	v_mfma_f32_32x32x16_bf16 v[48:63], v[132:135], v[224:227], v[48:63]
	ds_read_b64_tr_b16 v[224:225], v181 offset:0x2400
	ds_read_b64_tr_b16 v[226:227], v181 offset:0x2c00
	v_max_f32_e32 v251, v207, v207
	v_max_f32_e32 v250, v251, v250
	v_sub_f32_e32 v251, v207, v250
	v_mul_f32_e32 v251, 0x3dd53b94, v251
	s_waitcnt lgkmcnt(8)
	v_mfma_f32_32x32x16_bf16 v[48:63], v[154:157], v[232:235], v[48:63]
	ds_read_b64_tr_b16 v[232:233], v181 offset:0x3400
	ds_read_b64_tr_b16 v[234:235], v181 offset:0x3c00
	v_exp_f32_e32 v251, v251
	s_waitcnt lgkmcnt(8)
	v_mfma_f32_32x32x16_bf16 v[48:63], v[220:223], v[236:239], v[48:63]
	ds_read_b64_tr_b16 v[236:237], v181 offset:0x600
	ds_read_b64_tr_b16 v[238:239], v181 offset:0xe00
	s_waitcnt lgkmcnt(8)
	v_mfma_f32_32x32x16_bf16 v[32:47], v[128:131], v[240:243], v[32:47]
	ds_read_b64_tr_b16 v[240:241], v181 offset:0x1600
	ds_read_b64_tr_b16 v[242:243], v181 offset:0x1e00
	s_waitcnt lgkmcnt(8)
	v_mfma_f32_32x32x16_bf16 v[32:47], v[132:135], v[212:215], v[32:47]
	ds_read_b64_tr_b16 v[212:213], v181 offset:0x2600
	ds_read_b64_tr_b16 v[214:215], v181 offset:0x2e00
	s_waitcnt lgkmcnt(8)
	v_mfma_f32_32x32x16_bf16 v[32:47], v[154:157], v[224:227], v[32:47]
	ds_read_b64_tr_b16 v[224:225], v181 offset:0x3600
	ds_read_b64_tr_b16 v[226:227], v181 offset:0x3e00
	s_waitcnt lgkmcnt(8)
	v_mfma_f32_32x32x16_bf16 v[32:47], v[220:223], v[232:235], v[32:47]
	s_waitcnt lgkmcnt(6)
	v_mfma_f32_32x32x16_bf16 v[16:31], v[128:131], v[236:239], v[16:31]
	s_waitcnt lgkmcnt(4)
	v_mfma_f32_32x32x16_bf16 v[16:31], v[132:135], v[240:243], v[16:31]
	s_waitcnt lgkmcnt(2)
	v_mfma_f32_32x32x16_bf16 v[16:31], v[154:157], v[212:215], v[16:31]
	s_waitcnt lgkmcnt(0)
	v_mfma_f32_32x32x16_bf16 v[16:31], v[220:223], v[224:227], v[16:31]
	s_cmp_eq_u64 vcc, exec
	s_cselect_b64 s[6:7], -1, 0
	s_barrier
	s_waitcnt vmcnt(0)
	v_cndmask_b32_e64 v220, v251, 1.0, s[6:7]
	v_add_u32_e32 v129, 0x10800, v208
	v_cmp_gt_f32_e32 vcc, 1.0, v220
	s_waitcnt vmcnt(4)
	ds_write_b128 v185, v[136:139]
	s_waitcnt vmcnt(3)
	ds_write_b128 v186, v[140:143]
	s_waitcnt vmcnt(2)
	ds_write_b128 v187, v[146:149] offset:32768
	s_waitcnt vmcnt(1)
	ds_write_b128 v188, v[150:153] offset:32768
	s_waitcnt vmcnt(0)
	ds_write_b128 v129, v[158:161]
	s_cbranch_vccz .LBB0_766
	s_and_saveexec_b64 s[0:1], s[4:5]
	ds_write_b32 v183, v220 offset:128
	s_or_b64 exec, exec, s[0:1]
	s_waitcnt lgkmcnt(0)
	v_add_u32_e32 v129, v180, v144
	ds_read_b128 v[130:133], v129 offset:224
	ds_read_b128 v[134:137], v129 offset:192
	ds_read_b128 v[138:141], v129 offset:160
	ds_read_b128 v[146:149], v129 offset:128
	s_waitcnt lgkmcnt(3)
	v_pk_mul_f32 v[12:13], v[12:13], v[130:131]
	s_waitcnt lgkmcnt(2)
	v_pk_mul_f32 v[8:9], v[8:9], v[134:135]
	s_waitcnt lgkmcnt(1)
	v_pk_mul_f32 v[4:5], v[4:5], v[138:139]
	v_pk_mul_f32 v[14:15], v[14:15], v[132:133]
	v_pk_mul_f32 v[10:11], v[10:11], v[136:137]
	v_pk_mul_f32 v[6:7], v[6:7], v[140:141]
	s_waitcnt lgkmcnt(0)
	v_pk_mul_f32 v[2:3], v[2:3], v[148:149]
	v_pk_mul_f32 v[0:1], v[0:1], v[146:147]
	v_pk_mul_f32 v[60:61], v[60:61], v[130:131]
	v_pk_mul_f32 v[56:57], v[56:57], v[134:135]
	v_pk_mul_f32 v[52:53], v[52:53], v[138:139]
	v_pk_mul_f32 v[62:63], v[62:63], v[132:133]
	v_pk_mul_f32 v[58:59], v[58:59], v[136:137]
	v_pk_mul_f32 v[54:55], v[54:55], v[140:141]
	v_pk_mul_f32 v[50:51], v[50:51], v[148:149]
	v_pk_mul_f32 v[48:49], v[48:49], v[146:147]
	v_pk_mul_f32 v[44:45], v[44:45], v[130:131]
	v_pk_mul_f32 v[40:41], v[40:41], v[134:135]
	v_pk_mul_f32 v[36:37], v[36:37], v[138:139]
	v_pk_mul_f32 v[46:47], v[46:47], v[132:133]
	v_pk_mul_f32 v[42:43], v[42:43], v[136:137]
	v_pk_mul_f32 v[38:39], v[38:39], v[140:141]
	v_pk_mul_f32 v[34:35], v[34:35], v[148:149]
	v_pk_mul_f32 v[32:33], v[32:33], v[146:147]
	v_pk_mul_f32 v[28:29], v[28:29], v[130:131]
	v_pk_mul_f32 v[24:25], v[24:25], v[134:135]
	v_pk_mul_f32 v[20:21], v[20:21], v[138:139]
	v_pk_mul_f32 v[30:31], v[30:31], v[132:133]
	v_pk_mul_f32 v[26:27], v[26:27], v[136:137]
	v_pk_mul_f32 v[22:23], v[22:23], v[140:141]
	v_pk_mul_f32 v[18:19], v[18:19], v[148:149]
	v_pk_mul_f32 v[16:17], v[16:17], v[146:147]
.LBB0_766:
	v_cndmask_b32_e64 v207, v250, v207, s[6:7]
	v_mul_f32_e32 v146, 0xbdd53b94, v207
	v_fmamk_f32 v80, v80, 0x3dd53b94, v146
	v_exp_f32_e32 v128, v80
	v_fmamk_f32 v81, v81, 0x3dd53b94, v146
	v_fmamk_f32 v82, v82, 0x3dd53b94, v146
	v_fmamk_f32 v83, v83, 0x3dd53b94, v146
	v_fmamk_f32 v84, v84, 0x3dd53b94, v146
	v_fmamk_f32 v85, v85, 0x3dd53b94, v146
	v_fmamk_f32 v86, v86, 0x3dd53b94, v146
	v_fmamk_f32 v87, v87, 0x3dd53b94, v146
	v_fmamk_f32 v88, v88, 0x3dd53b94, v146
	v_fmamk_f32 v89, v89, 0x3dd53b94, v146
	v_fmamk_f32 v90, v90, 0x3dd53b94, v146
	v_fmamk_f32 v91, v91, 0x3dd53b94, v146
	v_fmamk_f32 v92, v92, 0x3dd53b94, v146
	v_fmamk_f32 v93, v93, 0x3dd53b94, v146
	v_fmamk_f32 v94, v94, 0x3dd53b94, v146
	v_fmamk_f32 v95, v95, 0x3dd53b94, v146
	v_fmamk_f32 v155, v64, 0x3dd53b94, v146
	v_fmamk_f32 v156, v65, 0x3dd53b94, v146
	v_fmamk_f32 v157, v66, 0x3dd53b94, v146
	v_fmamk_f32 v158, v67, 0x3dd53b94, v146
	v_fmamk_f32 v159, v68, 0x3dd53b94, v146
	v_fmamk_f32 v148, v69, 0x3dd53b94, v146
	v_fmamk_f32 v149, v70, 0x3dd53b94, v146
	v_fmamk_f32 v150, v71, 0x3dd53b94, v146
	v_fmamk_f32 v151, v72, 0x3dd53b94, v146
	v_fmamk_f32 v152, v73, 0x3dd53b94, v146
	v_fmamk_f32 v153, v74, 0x3dd53b94, v146
	v_fmamk_f32 v154, v75, 0x3dd53b94, v146
	v_fmamk_f32 v147, v76, 0x3dd53b94, v146
	v_exp_f32_e32 v143, v81
	v_exp_f32_e32 v129, v82
	v_exp_f32_e32 v142, v83
	v_exp_f32_e32 v130, v84
	v_exp_f32_e32 v141, v85
	v_exp_f32_e32 v131, v86
	v_exp_f32_e32 v140, v87
	v_exp_f32_e32 v132, v88
	v_exp_f32_e32 v139, v89
	v_exp_f32_e32 v133, v90
	v_exp_f32_e32 v138, v91
	v_exp_f32_e32 v134, v92
	v_exp_f32_e32 v137, v93
	v_exp_f32_e32 v135, v94
	v_exp_f32_e32 v136, v95
	v_fmamk_f32 v160, v77, 0x3dd53b94, v146
	v_fmamk_f32 v161, v78, 0x3dd53b94, v146
	v_fmac_f32_e32 v146, 0x3dd53b94, v79
	s_waitcnt lgkmcnt(0)
	s_barrier
	ds_read_b128 v[64:67], v189 offset:32768
	ds_read_b128 v[68:71], v189 offset:40960
	ds_read_b128 v[240:243], v191 offset:32768
	ds_read_b128 v[244:247], v191 offset:40960
	ds_read_b128 v[248:251], v193 offset:32768
	s_cmp_lt_u32 s9, 2
	s_cselect_b32 s100, s46, s68
	s_add_i32 s100, s100, s8
	s_add_i32 s100, s100, 64
	s_ashr_i32 s101, s100, 31
	s_waitcnt lgkmcnt(4)
	v_mfma_f32_32x32x16_bf16 v[80:95], v[64:67], v[124:127], 0
	v_exp_f32_e32 v212, v154
	v_add_f32_e32 v154, 0, v128
	v_add_f32_e32 v154, v143, v154
	v_add_f32_e32 v154, v129, v154
	s_waitcnt lgkmcnt(3)
	v_mfma_f32_32x32x16_bf16 v[64:79], v[68:71], v[124:127], 0
	v_add_f32_e32 v154, v142, v154
	v_add_f32_e32 v154, v130, v154
	v_add_f32_e32 v154, v141, v154
	v_add_f32_e32 v154, v131, v154
	v_add_f32_e32 v154, v140, v154
	s_waitcnt lgkmcnt(2)
	v_mfma_f32_32x32x16_bf16 v[80:95], v[240:243], v[120:123], v[80:95]
	ds_read_b128 v[240:243], v193 offset:40960
	v_add_f32_e32 v154, v132, v154
	v_add_f32_e32 v154, v139, v154
	v_add_f32_e32 v154, v133, v154
	v_add_f32_e32 v154, v138, v154
	v_add_f32_e32 v154, v134, v154
	s_waitcnt lgkmcnt(2)
	v_mfma_f32_32x32x16_bf16 v[64:79], v[244:247], v[120:123], v[64:79]
	ds_read_b128 v[244:247], v195 offset:32768
	v_exp_f32_e32 v155, v155
	v_exp_f32_e32 v156, v156
	v_add_f32_e32 v154, v137, v154
	s_waitcnt lgkmcnt(2)
	v_mfma_f32_32x32x16_bf16 v[80:95], v[248:251], v[116:119], v[80:95]
	ds_read_b128 v[248:251], v195 offset:40960
	v_exp_f32_e32 v157, v157
	v_add_f32_e32 v154, v135, v154
	v_exp_f32_e32 v158, v158
	s_waitcnt lgkmcnt(2)
	v_mfma_f32_32x32x16_bf16 v[64:79], v[240:243], v[116:119], v[64:79]
	ds_read_b128 v[240:243], v196 offset:32768
	v_add_f32_e32 v154, v136, v154
	v_exp_f32_e32 v159, v159
	v_add_f32_e32 v154, v155, v154
	v_add_f32_e32 v154, v156, v154
	s_waitcnt lgkmcnt(2)
	v_mfma_f32_32x32x16_bf16 v[80:95], v[244:247], v[112:115], v[80:95]
	ds_read_b128 v[244:247], v196 offset:40960
	v_exp_f32_e32 v148, v148
	v_exp_f32_e32 v149, v149
	v_add_f32_e32 v154, v157, v154
	s_waitcnt lgkmcnt(2)
	v_mfma_f32_32x32x16_bf16 v[64:79], v[248:251], v[112:115], v[64:79]
	ds_read_b128 v[248:251], v194 offset:32768
	v_exp_f32_e32 v150, v150
	v_add_f32_e32 v154, v158, v154
	v_exp_f32_e32 v151, v151
	s_waitcnt lgkmcnt(2)
	v_mfma_f32_32x32x16_bf16 v[80:95], v[240:243], v[108:111], v[80:95]
	ds_read_b128 v[240:243], v194 offset:40960
	v_add_f32_e32 v154, v159, v154
	v_exp_f32_e32 v152, v152
	v_add_f32_e32 v154, v148, v154
	v_add_f32_e32 v154, v149, v154
	s_waitcnt lgkmcnt(2)
	v_mfma_f32_32x32x16_bf16 v[64:79], v[244:247], v[108:111], v[64:79]
	ds_read_b128 v[244:247], v192 offset:32768
	v_exp_f32_e32 v153, v153
	v_add_f32_e32 v154, v150, v154
	v_exp_f32_e32 v147, v147
	s_waitcnt lgkmcnt(2)
	v_mfma_f32_32x32x16_bf16 v[80:95], v[248:251], v[104:107], v[80:95]
	ds_read_b128 v[248:251], v192 offset:40960
	v_add_f32_e32 v154, v151, v154
	v_exp_f32_e32 v160, v160
	v_add_f32_e32 v154, v152, v154
	v_add_f32_e32 v154, v153, v154
	s_waitcnt lgkmcnt(2)
	v_mfma_f32_32x32x16_bf16 v[64:79], v[240:243], v[104:107], v[64:79]
	ds_read_b128 v[240:243], v190 offset:32768
	v_exp_f32_e32 v161, v161
	v_exp_f32_e32 v146, v146
	v_add_f32_e32 v154, v212, v154
	s_waitcnt lgkmcnt(2)
	v_mfma_f32_32x32x16_bf16 v[80:95], v[244:247], v[100:103], v[80:95]
	ds_read_b128 v[244:247], v190 offset:40960
	v_add_f32_e32 v154, v147, v154
	v_add_f32_e32 v154, v160, v154
	v_add_f32_e32 v154, v161, v154
	v_cvt_pk_bf16_f32 v128, v128, v143
	v_cvt_pk_bf16_f32 v129, v129, v142
	s_waitcnt lgkmcnt(2)
	v_mfma_f32_32x32x16_bf16 v[64:79], v[248:251], v[100:103], v[64:79]
	ds_read_b128 v[248:251], v199
	v_cvt_pk_bf16_f32 v130, v130, v141
	v_cvt_pk_bf16_f32 v131, v131, v140
	v_cvt_pk_bf16_f32 v132, v132, v139
	v_cvt_pk_bf16_f32 v133, v133, v138
	v_add_f32_e32 v222, v146, v154
	s_waitcnt lgkmcnt(2)
	v_mfma_f32_32x32x16_bf16 v[80:95], v[240:243], v[96:99], v[80:95]
	v_mov_b32_e32 v223, v222
	s_nop 1
	v_permlane32_swap_b32_e32 v222, v223
	v_permlane32_swap_b32_e32 v128, v130
	v_cvt_pk_bf16_f32 v134, v134, v137
	v_cvt_pk_bf16_f32 v135, v135, v136
	s_waitcnt lgkmcnt(1)
	v_mfma_f32_32x32x16_bf16 v[64:79], v[244:247], v[96:99], v[64:79]
	ds_read_b128 v[244:247], v199 offset:4096
	ds_read_b128 v[240:243], v182
	v_cvt_pk_bf16_f32 v154, v155, v156
	v_cvt_pk_bf16_f32 v155, v157, v158
	v_cvt_pk_bf16_f32 v156, v159, v148
	v_cvt_pk_bf16_f32 v157, v149, v150
	v_cvt_pk_bf16_f32 v224, v151, v152
	s_waitcnt lgkmcnt(0)
	v_mfma_f32_32x32x16_bf16 v[80:95], v[248:251], v[240:243], v[80:95]
	ds_read_b128 v[248:251], v201
	v_cvt_pk_bf16_f32 v225, v153, v212
	v_cvt_pk_bf16_f32 v226, v147, v160
	v_cvt_pk_bf16_f32 v227, v161, v146
	v_permlane32_swap_b32_e32 v129, v131
	v_permlane32_swap_b32_e32 v132, v134
	v_mfma_f32_32x32x16_bf16 v[64:79], v[244:247], v[240:243], v[64:79]
	ds_read_b128 v[244:247], v201 offset:4096
	ds_read_b128 v[240:243], v182 offset:1024
	v_permlane32_swap_b32_e32 v133, v135
	v_permlane32_swap_b32_e32 v154, v156
	v_permlane32_swap_b32_e32 v155, v157
	v_permlane32_swap_b32_e32 v224, v226
	v_permlane32_swap_b32_e32 v225, v227
	s_waitcnt lgkmcnt(0)
	v_mfma_f32_32x32x16_bf16 v[80:95], v[248:251], v[240:243], v[80:95]
	ds_read_b128 v[248:251], v203
	v_lshl_add_u64 v[136:137], s[100:101], 0, v[162:163]
	v_mul_lo_u32 v138, v137, s40
	v_mul_lo_u32 v139, v136, s41
	v_mad_u64_u32 v[136:137], s[6:7], v136, s40, 0
	v_add3_u32 v137, v137, v139, v138
	v_mfma_f32_32x32x16_bf16 v[64:79], v[244:247], v[240:243], v[64:79]
	ds_read_b128 v[244:247], v203 offset:4096
	ds_read_b128 v[240:243], v182 offset:2048
	v_lshl_add_u64 v[138:139], v[166:167], 0, s[100:101]
	v_mul_lo_u32 v140, v139, s40
	v_mul_lo_u32 v141, v138, s41
	v_mad_u64_u32 v[138:139], s[6:7], v138, s40, 0
	v_add3_u32 v139, v139, v141, v140
	s_waitcnt lgkmcnt(0)
	v_mfma_f32_32x32x16_bf16 v[80:95], v[248:251], v[240:243], v[80:95]
	ds_read_b128 v[248:251], v205
	v_lshlrev_b64 v[146:147], 1, v[136:137]
	v_lshlrev_b64 v[148:149], 1, v[138:139]
	v_lshl_add_u64 v[158:159], s[100:101], 0, v[164:165]
	v_lshl_add_u64 v[136:137], v[168:169], 0, v[146:147]
	v_lshl_add_u64 v[140:141], v[168:169], 0, v[148:149]
	v_mfma_f32_32x32x16_bf16 v[64:79], v[244:247], v[240:243], v[64:79]
	ds_read_b128 v[244:247], v205 offset:4096
	ds_read_b128 v[240:243], v182 offset:3072
	ds_read_b64_tr_b16 v[232:233], v184 offset:0
	ds_read_b64_tr_b16 v[234:235], v184 offset:0x800
	ds_read_b64_tr_b16 v[236:237], v184 offset:0x1000
	ds_read_b64_tr_b16 v[238:239], v184 offset:0x1800
	v_lshl_add_u64 v[146:147], v[170:171], 0, v[146:147]
	v_lshl_add_u64 v[150:151], v[170:171], 0, v[148:149]
	v_mad_u64_u32 v[160:161], s[100:101], v158, s3, v[172:173]
	v_mad_i32_i24 v161, v159, s3, v161
	s_waitcnt lgkmcnt(4)
	v_mfma_f32_32x32x16_bf16 v[80:95], v[248:251], v[240:243], v[80:95]
	v_mfma_f32_32x32x16_bf16 v[64:79], v[244:247], v[240:243], v[64:79]
	ds_read_b64_tr_b16 v[240:241], v184 offset:0x2000
	ds_read_b64_tr_b16 v[242:243], v184 offset:0x2800
	ds_read_b64_tr_b16 v[244:245], v184 offset:0x3000
	ds_read_b64_tr_b16 v[246:247], v184 offset:0x3800
	global_load_dwordx4 v[136:139], v[136:137], off
	global_load_dwordx4 v[140:143], v[140:141], off
	global_load_dwordx4 v[146:149], v[146:147], off
	global_load_dwordx4 v[150:153], v[150:151], off
	global_load_dwordx4 v[158:161], v[160:161], off
	s_waitcnt lgkmcnt(6)
	v_mfma_f32_32x32x16_bf16 v[0:15], v[128:131], v[232:235], v[0:15]
	ds_read_b64_tr_b16 v[232:233], v184 offset:0x200
	ds_read_b64_tr_b16 v[234:235], v184 offset:0xa00
	s_waitcnt lgkmcnt(6)
	v_mfma_f32_32x32x16_bf16 v[0:15], v[132:135], v[236:239], v[0:15]
	ds_read_b64_tr_b16 v[236:237], v184 offset:0x1200
	ds_read_b64_tr_b16 v[238:239], v184 offset:0x1a00
	v_max_f32_e32 v250, v81, v81
	v_max_f32_e32 v251, v80, v80
	v_max_f32_e32 v250, v251, v250
	v_max3_f32 v250, v250, v82, v83
	v_max3_f32 v250, v250, v84, v85
	s_waitcnt lgkmcnt(6)
	v_mfma_f32_32x32x16_bf16 v[0:15], v[154:157], v[240:243], v[0:15]
	ds_read_b64_tr_b16 v[240:241], v184 offset:0x2200
	ds_read_b64_tr_b16 v[242:243], v184 offset:0x2a00
	v_max3_f32 v250, v250, v86, v87
	v_max3_f32 v250, v250, v88, v89
	v_max3_f32 v250, v250, v90, v91
	v_max3_f32 v250, v250, v92, v93
	v_max3_f32 v250, v250, v94, v95
	s_waitcnt lgkmcnt(6)
	v_mfma_f32_32x32x16_bf16 v[0:15], v[224:227], v[244:247], v[0:15]
	ds_read_b64_tr_b16 v[244:245], v184 offset:0x3200
	ds_read_b64_tr_b16 v[246:247], v184 offset:0x3a00
	v_max3_f32 v250, v250, v64, v65
	v_max3_f32 v250, v250, v66, v67
	v_max3_f32 v250, v250, v68, v69
	v_max3_f32 v250, v250, v70, v71
	v_max3_f32 v250, v250, v72, v73
	s_waitcnt lgkmcnt(6)
	v_mfma_f32_32x32x16_bf16 v[48:63], v[128:131], v[232:235], v[48:63]
	ds_read_b64_tr_b16 v[232:233], v184 offset:0x400
	ds_read_b64_tr_b16 v[234:235], v184 offset:0xc00
	v_max3_f32 v250, v250, v74, v75
	v_max3_f32 v250, v250, v76, v77
	v_max3_f32 v250, v250, v78, v79
	v_mov_b32_e32 v251, v250
	s_nop 1
	v_permlane32_swap_b32_e32 v250, v251
	s_waitcnt lgkmcnt(6)
	v_mfma_f32_32x32x16_bf16 v[48:63], v[132:135], v[236:239], v[48:63]
	ds_read_b64_tr_b16 v[236:237], v184 offset:0x1400
	ds_read_b64_tr_b16 v[238:239], v184 offset:0x1c00
	v_max_f32_e32 v251, v251, v251
	v_max_f32_e32 v250, v250, v250
	v_max_f32_e32 v250, v250, v251
	v_sub_f32_e32 v251, v250, v207
	v_cmp_ge_f32_e32 vcc, s94, v251
	s_waitcnt lgkmcnt(6)
	v_mfma_f32_32x32x16_bf16 v[48:63], v[154:157], v[240:243], v[48:63]
	ds_read_b64_tr_b16 v[240:241], v184 offset:0x2400
	ds_read_b64_tr_b16 v[242:243], v184 offset:0x2c00
	v_max_f32_e32 v251, v207, v207
	v_max_f32_e32 v250, v251, v250
	v_sub_f32_e32 v251, v207, v250
	v_mul_f32_e32 v251, 0x3dd53b94, v251
	s_waitcnt lgkmcnt(6)
	v_mfma_f32_32x32x16_bf16 v[48:63], v[224:227], v[244:247], v[48:63]
	ds_read_b64_tr_b16 v[244:245], v184 offset:0x3400
	ds_read_b64_tr_b16 v[246:247], v184 offset:0x3c00
	v_exp_f32_e32 v251, v251
	s_waitcnt lgkmcnt(6)
	v_mfma_f32_32x32x16_bf16 v[32:47], v[128:131], v[232:235], v[32:47]
	ds_read_b64_tr_b16 v[232:233], v184 offset:0x600
	ds_read_b64_tr_b16 v[234:235], v184 offset:0xe00
	s_waitcnt lgkmcnt(6)
	v_mfma_f32_32x32x16_bf16 v[32:47], v[132:135], v[236:239], v[32:47]
	ds_read_b64_tr_b16 v[236:237], v184 offset:0x1600
	ds_read_b64_tr_b16 v[238:239], v184 offset:0x1e00
	s_waitcnt lgkmcnt(6)
	v_mfma_f32_32x32x16_bf16 v[32:47], v[154:157], v[240:243], v[32:47]
	ds_read_b64_tr_b16 v[240:241], v184 offset:0x2600
	ds_read_b64_tr_b16 v[242:243], v184 offset:0x2e00
	s_waitcnt lgkmcnt(6)
	v_mfma_f32_32x32x16_bf16 v[32:47], v[224:227], v[244:247], v[32:47]
	ds_read_b64_tr_b16 v[244:245], v184 offset:0x3600
	ds_read_b64_tr_b16 v[246:247], v184 offset:0x3e00
	s_waitcnt lgkmcnt(6)
	v_mfma_f32_32x32x16_bf16 v[16:31], v[128:131], v[232:235], v[16:31]
	s_waitcnt lgkmcnt(4)
	v_mfma_f32_32x32x16_bf16 v[16:31], v[132:135], v[236:239], v[16:31]
	s_waitcnt lgkmcnt(2)
	v_mfma_f32_32x32x16_bf16 v[16:31], v[154:157], v[240:243], v[16:31]
	s_waitcnt lgkmcnt(0)
	v_mfma_f32_32x32x16_bf16 v[16:31], v[224:227], v[244:247], v[16:31]
	s_cmp_eq_u64 vcc, exec
	s_cselect_b64 s[6:7], -1, 0
	s_barrier
	s_waitcnt vmcnt(0)
	v_cndmask_b32_e64 v221, v251, 1.0, s[6:7]
	v_cmp_gt_f32_e32 vcc, 1.0, v221
	s_waitcnt vmcnt(4)
	ds_write_b128 v185, v[136:139] offset:16384
	s_waitcnt vmcnt(3)
	ds_write_b128 v186, v[140:143] offset:16384
	s_waitcnt vmcnt(2)
	ds_write_b128 v187, v[146:149] offset:49152
	s_waitcnt vmcnt(1)
	ds_write_b128 v188, v[150:153] offset:49152
	s_waitcnt vmcnt(0)
	ds_write_b128 v209, v[158:161]
	s_cbranch_vccz .LBB0_770
	s_and_saveexec_b64 s[0:1], s[4:5]
	ds_write_b32 v183, v221 offset:128
	s_or_b64 exec, exec, s[0:1]
	s_waitcnt lgkmcnt(0)
	v_add_u32_e32 v129, v180, v144
	ds_read_b128 v[130:133], v129 offset:224
	ds_read_b128 v[134:137], v129 offset:192
	ds_read_b128 v[138:141], v129 offset:160
	ds_read_b128 v[146:149], v129 offset:128
	s_waitcnt lgkmcnt(3)
	v_pk_mul_f32 v[12:13], v[12:13], v[130:131]
	s_waitcnt lgkmcnt(2)
	v_pk_mul_f32 v[8:9], v[8:9], v[134:135]
	s_waitcnt lgkmcnt(1)
	v_pk_mul_f32 v[4:5], v[4:5], v[138:139]
	v_pk_mul_f32 v[14:15], v[14:15], v[132:133]
	v_pk_mul_f32 v[10:11], v[10:11], v[136:137]
	v_pk_mul_f32 v[6:7], v[6:7], v[140:141]
	s_waitcnt lgkmcnt(0)
	v_pk_mul_f32 v[2:3], v[2:3], v[148:149]
	v_pk_mul_f32 v[0:1], v[0:1], v[146:147]
	v_pk_mul_f32 v[60:61], v[60:61], v[130:131]
	v_pk_mul_f32 v[56:57], v[56:57], v[134:135]
	v_pk_mul_f32 v[52:53], v[52:53], v[138:139]
	v_pk_mul_f32 v[62:63], v[62:63], v[132:133]
	v_pk_mul_f32 v[58:59], v[58:59], v[136:137]
	v_pk_mul_f32 v[54:55], v[54:55], v[140:141]
	v_pk_mul_f32 v[50:51], v[50:51], v[148:149]
	v_pk_mul_f32 v[48:49], v[48:49], v[146:147]
	v_pk_mul_f32 v[44:45], v[44:45], v[130:131]
	v_pk_mul_f32 v[40:41], v[40:41], v[134:135]
	v_pk_mul_f32 v[36:37], v[36:37], v[138:139]
	v_pk_mul_f32 v[46:47], v[46:47], v[132:133]
	v_pk_mul_f32 v[42:43], v[42:43], v[136:137]
	v_pk_mul_f32 v[38:39], v[38:39], v[140:141]
	v_pk_mul_f32 v[34:35], v[34:35], v[148:149]
	v_pk_mul_f32 v[32:33], v[32:33], v[146:147]
	v_pk_mul_f32 v[28:29], v[28:29], v[130:131]
	v_pk_mul_f32 v[24:25], v[24:25], v[134:135]
	v_pk_mul_f32 v[20:21], v[20:21], v[138:139]
	v_pk_mul_f32 v[30:31], v[30:31], v[132:133]
	v_pk_mul_f32 v[26:27], v[26:27], v[136:137]
	v_pk_mul_f32 v[22:23], v[22:23], v[140:141]
	v_pk_mul_f32 v[18:19], v[18:19], v[148:149]
	v_pk_mul_f32 v[16:17], v[16:17], v[146:147]
.LBB0_770:
	v_cndmask_b32_e64 v207, v250, v207, s[6:7]
	v_mul_f32_e32 v134, 0xbdd53b94, v207
	v_mov_b32_e32 v135, v134
	v_fmamk_f32 v80, v80, 0x3dd53b94, v134
	v_fmamk_f32 v81, v81, 0x3dd53b94, v134
	v_fmamk_f32 v82, v82, 0x3dd53b94, v134
	v_fmamk_f32 v83, v83, 0x3dd53b94, v134
	v_fmamk_f32 v84, v84, 0x3dd53b94, v134
	v_fmamk_f32 v85, v85, 0x3dd53b94, v134
	v_fmamk_f32 v86, v86, 0x3dd53b94, v134
	v_fmamk_f32 v87, v87, 0x3dd53b94, v134
	v_fmamk_f32 v88, v88, 0x3dd53b94, v134
	v_fmamk_f32 v89, v89, 0x3dd53b94, v134
	v_fmamk_f32 v90, v90, 0x3dd53b94, v134
	v_fmamk_f32 v91, v91, 0x3dd53b94, v134
	v_fmamk_f32 v92, v92, 0x3dd53b94, v134
	v_fmamk_f32 v93, v93, 0x3dd53b94, v134
	v_fmamk_f32 v94, v94, 0x3dd53b94, v134
	v_fmac_f32_e32 v135, 0x3dd53b94, v95
	v_exp_f32_e32 v159, v80
	v_exp_f32_e32 v161, v81
	v_exp_f32_e32 v157, v82
	v_exp_f32_e32 v160, v83
	v_exp_f32_e32 v156, v84
	v_exp_f32_e32 v158, v85
	v_exp_f32_e32 v154, v86
	v_exp_f32_e32 v155, v87
	v_exp_f32_e32 v151, v88
	v_exp_f32_e32 v153, v89
	v_exp_f32_e32 v150, v90
	v_exp_f32_e32 v152, v91
	v_exp_f32_e32 v147, v92
	v_exp_f32_e32 v149, v93
	v_exp_f32_e32 v146, v94
	v_exp_f32_e32 v148, v135
	v_pk_fma_f32 v[140:141], v[64:65], s[76:77], v[134:135] op_sel_hi:[1,0,0]
	v_add_f32_e32 v64, v218, v219
	v_fmac_f32_e32 v64, v206, v197
	v_add_f32_e32 v197, v222, v223
	s_addk_i32 s8, 0x80
	s_add_i32 s24, s24, 2
	v_pk_fma_f32 v[138:139], v[66:67], s[76:77], v[134:135] op_sel_hi:[1,0,0]
	v_pk_fma_f32 v[132:133], v[68:69], s[76:77], v[134:135] op_sel_hi:[1,0,0]
	v_pk_fma_f32 v[130:131], v[70:71], s[76:77], v[134:135] op_sel_hi:[1,0,0]
	v_pk_fma_f32 v[128:129], v[72:73], s[76:77], v[134:135] op_sel_hi:[1,0,0]
	v_pk_fma_f32 v[142:143], v[74:75], s[76:77], v[134:135] op_sel_hi:[1,0,0]
	v_pk_fma_f32 v[136:137], v[76:77], s[76:77], v[134:135] op_sel_hi:[1,0,0]
	v_pk_fma_f32 v[134:135], v[78:79], s[76:77], v[134:135] op_sel_hi:[1,0,0]
	v_fmac_f32_e32 v197, v64, v220
	s_cmp_ge_u32 s24, s91
	s_waitcnt lgkmcnt(0)
	s_barrier
	s_cbranch_scc1 .LBB0_772
	v_mov_b32_e32 v206, v221
	s_branch .LBB0_762

	.amdhsa_kernel _Z6mk_fwd6Params
		.amdhsa_group_segment_fixed_size 0
		.amdhsa_private_segment_fixed_size 0
		.amdhsa_kernarg_size 472
		.amdhsa_user_sgpr_count 2
		.amdhsa_user_sgpr_dispatch_ptr 0
		.amdhsa_user_sgpr_queue_ptr 0
		.amdhsa_user_sgpr_kernarg_segment_ptr 1
		.amdhsa_user_sgpr_dispatch_id 0
		.amdhsa_user_sgpr_kernarg_preload_length 0
		.amdhsa_user_sgpr_kernarg_preload_offset 0
		.amdhsa_user_sgpr_private_segment_size 0
		.amdhsa_uses_dynamic_stack 0
		.amdhsa_enable_private_segment 0
		.amdhsa_system_sgpr_workgroup_id_x 1
		.amdhsa_system_sgpr_workgroup_id_y 0
		.amdhsa_system_sgpr_workgroup_id_z 0
		.amdhsa_system_sgpr_workgroup_info 0
		.amdhsa_system_vgpr_workitem_id 2
		.amdhsa_next_free_vgpr 256
		.amdhsa_next_free_sgpr 102
		.amdhsa_accum_offset 256
		.amdhsa_reserve_vcc 1
		.amdhsa_float_round_mode_32 0
		.amdhsa_float_round_mode_16_64 0
		.amdhsa_float_denorm_mode_32 3
		.amdhsa_float_denorm_mode_16_64 3
		.amdhsa_dx10_clamp 1
		.amdhsa_ieee_mode 1
		.amdhsa_fp16_overflow 0
		.amdhsa_tg_split 0
		.amdhsa_exception_fp_ieee_invalid_op 0
		.amdhsa_exception_fp_denorm_src 0
		.amdhsa_exception_fp_ieee_div_zero 0
		.amdhsa_exception_fp_ieee_overflow 0
		.amdhsa_exception_fp_ieee_underflow 0
		.amdhsa_exception_fp_ieee_inexact 0
		.amdhsa_exception_int_div_zero 0
	.end_amdhsa_kernel

amdhsa.kernels:
  - .agpr_count:     0
    .args:
      - .offset:         0
        .size:           216
        .value_kind:     by_value
      - .offset:         216
        .size:           4
        .value_kind:     hidden_block_count_x
      - .offset:         220
        .size:           4
        .value_kind:     hidden_block_count_y
      - .offset:         224
        .size:           4
        .value_kind:     hidden_block_count_z
      - .offset:         228
        .size:           2
        .value_kind:     hidden_group_size_x
      - .offset:         230
        .size:           2
        .value_kind:     hidden_group_size_y
      - .offset:         232
        .size:           2
        .value_kind:     hidden_group_size_z
      - .offset:         234
        .size:           2
        .value_kind:     hidden_remainder_x
      - .offset:         236
        .size:           2
        .value_kind:     hidden_remainder_y
      - .offset:         238
        .size:           2
        .value_kind:     hidden_remainder_z
      - .offset:         256
        .size:           8
        .value_kind:     hidden_global_offset_x
      - .offset:         264
        .size:           8
        .value_kind:     hidden_global_offset_y
      - .offset:         272
        .size:           8
        .value_kind:     hidden_global_offset_z
      - .offset:         280
        .size:           2
        .value_kind:     hidden_grid_dims
      - .offset:         304
        .size:           8
        .value_kind:     hidden_multigrid_sync_arg
      - .offset:         336
        .size:           4
        .value_kind:     hidden_dynamic_lds_size
    .group_segment_fixed_size: 0
    .kernarg_segment_align: 8
    .kernarg_segment_size: 472
    .language:       OpenCL C
    .language_version:
      - 2
      - 0
    .max_flat_workgroup_size: 512
    .name:           _Z6mk_fwd6Params
    .private_segment_fixed_size: 0
    .sgpr_count:     108
    .sgpr_spill_count: 203
    .symbol:         _Z6mk_fwd6Params.kd
    .uniform_work_group_size: 1
    .uses_dynamic_stack: false
    .vgpr_count:     256
    .vgpr_spill_count: 0
    .wavefront_size: 64
